# nt hint also on the read-once residual loads of the GEMM2 epilogue
# baseline (speedup 1.0000x reference)
; __device__ __forceinline__ unsigned cvt_pk_bf16(float lo, float hi) { unsigned r; asm volatile("v_cvt_pk_bf16_f32 %0, %1, %2" : "=v"(r) : "v"(lo), "v"(hi)); return r; }
;     __device__ __forceinline__ void operator()(const f32x4 (&acc)[2][2][4][2], const Unit& u, int wr, int wc, int fr, int fq) const {
;     ...
;         for (int ai = 0; ai < 2; ++ai) { u32x2 xw4[4][2][2];
; #pragma unroll
;             for (int m = 0; m < 4; ++m)
; #pragma unroll
;                 for (int bj = 0; bj < 2; ++bj)
; #pragma unroll
;                     for (int n = 0; n < 2; ++n) xw4[m][bj][n] = *(const u32x2*)(H1B + (size_t)(row0 + ai * HALF + m * 16) * 4096 + col0 + bj * HALF + n * 16);
; #pragma unroll
;             for (int m = 0; m < 4; ++m) { const int row = row0 + ai * HALF + m * 16; const float s = sc8[ai][m];
;                 float ss = 0.f;
; #pragma unroll
;                 for (int bj = 0; bj < 2; ++bj)
; #pragma unroll
;                     for (int n = 0; n < 2; ++n) { const int c = col0 + bj * HALF + n * 16; bf16_t* hp = H1B + (size_t)row * 4096 + c;
;                         const u32x2 xw = xw4[m][bj][n]; f32x4 x; x[0] = __builtin_bit_cast(float, xw.x << 16); x[1] = __builtin_bit_cast(float, xw.x & 0xffff0000u); x[2] = __builtin_bit_cast(float, xw.y << 16); x[3] = __builtin_bit_cast(float, xw.y & 0xffff0000u);
;                         const f32x4 v = x + acc[ai][bj][m][n] * s;
;                         u32x2 w; w.x = cvt_pk_bf16(v[0], v[1]); w.y = cvt_pk_bf16(v[2], v[3]); *(u32x2*)hp = w;
;                         ss += (v[0] * v[0] + v[1] * v[1]) + (v[2] * v[2] + v[3] * v[3]); }
;                 ss += __shfl_xor(ss, 16); ss += __shfl_xor(ss, 32);
;                 if (fq == 0) SSQ2[(size_t)row * 64 + u.pn * 4 + wc] = ss; } }
.LBB0_2492:
	v_ashrrev_i32_e32 v5, 31, v4
	v_lshlrev_b64 v[212:213], 1, v[4:5]
	v_lshl_add_u64 v[164:165], s[22:23], 0, v[212:213]
	v_lshlrev_b64 v[214:215], 13, v[146:147]
	v_lshl_add_u64 v[150:151], v[164:165], 0, v[214:215]
	global_load_dwordx2 v[216:217], v[150:151], off
	global_load_dwordx2 v[218:219], v[150:151], off offset:32
	global_load_dwordx2 v[220:221], v[150:151], off offset:256
	global_load_dwordx2 v[222:223], v[148:149], off
	global_load_dwordx2 v[224:225], v[150:151], off offset:288
	v_or_b32_e32 v190, 16, v146
	v_or_b32_e32 v174, 32, v146
	v_or_b32_e32 v166, 48, v146
	v_add_u32_e32 v160, 0x80, v146
	v_add_u32_e32 v156, 0x90, v146
	v_add_u32_e32 v152, 0xa0, v146
	v_add_u32_e32 v148, 0xb0, v146
	v_ashrrev_i32_e32 v191, 31, v190
	v_ashrrev_i32_e32 v175, 31, v174
	v_ashrrev_i32_e32 v167, 31, v166
	v_ashrrev_i32_e32 v161, 31, v160
	v_ashrrev_i32_e32 v157, 31, v156
	v_ashrrev_i32_e32 v153, 31, v152
	v_ashrrev_i32_e32 v149, 31, v148
	v_lshl_add_u64 v[150:151], v[190:191], 3, s[18:19]
	v_lshl_add_u64 v[154:155], v[174:175], 3, s[18:19]
	v_lshl_add_u64 v[158:159], v[166:167], 3, s[18:19]
	v_lshl_add_u64 v[162:163], v[160:161], 3, s[18:19]
	v_lshl_add_u64 v[170:171], v[156:157], 3, s[18:19]
	v_lshl_add_u64 v[172:173], v[152:153], 3, s[18:19]
	v_lshlrev_b64 v[206:207], 13, v[190:191]
	v_lshlrev_b64 v[194:195], 13, v[174:175]
	v_lshl_add_u64 v[176:177], v[148:149], 3, s[18:19]
	v_lshlrev_b64 v[178:179], 13, v[166:167]
	global_load_dwordx2 v[198:199], v[150:151], off
	global_load_dwordx2 v[184:185], v[154:155], off
	global_load_dwordx2 v[168:169], v[158:159], off
	s_nop 0
	global_load_dwordx2 v[162:163], v[162:163], off
	s_nop 0
	global_load_dwordx2 v[158:159], v[170:171], off
	global_load_dwordx2 v[154:155], v[172:173], off
	global_load_dwordx2 v[150:151], v[176:177], off
	v_lshl_add_u64 v[170:171], v[164:165], 0, v[206:207]
	v_lshl_add_u64 v[172:173], v[164:165], 0, v[194:195]
	v_lshl_add_u64 v[226:227], v[164:165], 0, v[178:179]
	global_load_dwordx2 v[208:209], v[170:171], off nt
	global_load_dwordx2 v[204:205], v[170:171], off offset:32 nt
	global_load_dwordx2 v[202:203], v[170:171], off offset:256 nt
	global_load_dwordx2 v[200:201], v[170:171], off offset:288 nt
	global_load_dwordx2 v[196:197], v[172:173], off nt
	global_load_dwordx2 v[192:193], v[172:173], off offset:32 nt
	global_load_dwordx2 v[188:189], v[172:173], off offset:256 nt
	global_load_dwordx2 v[186:187], v[172:173], off offset:288 nt
	global_load_dwordx2 v[180:181], v[226:227], off nt
	global_load_dwordx2 v[176:177], v[226:227], off offset:32 nt
	s_nop 0
	global_load_dwordx2 v[172:173], v[226:227], off offset:256 nt
	global_load_dwordx2 v[170:171], v[226:227], off offset:288 nt
	v_lshl_add_u64 v[214:215], s[22:23], 0, v[214:215]
	v_lshl_add_u64 v[212:213], v[214:215], 0, v[212:213]
	s_waitcnt vmcnt(0)
	v_lshlrev_b32_e32 v214, 16, v216
	v_and_b32_e32 v215, 0xffff0000, v216
	v_lshlrev_b32_e32 v216, 16, v217
	v_and_b32_e32 v217, 0xffff0000, v217
	v_lshlrev_b32_e32 v226, 16, v218
	v_and_b32_e32 v227, 0xffff0000, v218
	v_lshlrev_b32_e32 v218, 16, v219
	v_and_b32_e32 v219, 0xffff0000, v219
	v_pk_fma_f32 v[132:133], v[132:133], v[222:223], v[216:217] op_sel:[0,1,0]
	v_pk_fma_f32 v[130:131], v[130:131], v[222:223], v[214:215] op_sel:[0,1,0]
	v_pk_fma_f32 v[128:129], v[128:129], v[222:223], v[218:219] op_sel:[0,1,0]
	v_pk_fma_f32 v[126:127], v[126:127], v[222:223], v[226:227] op_sel:[0,1,0]
	v_cvt_pk_bf16_f32 v214, v130, v131
	v_cvt_pk_bf16_f32 v215, v132, v133
	v_mul_f32_e32 v3, v131, v131
	v_mul_f32_e32 v131, v133, v133
	v_mul_f32_e32 v133, v127, v127
	v_mul_f32_e32 v216, v129, v129
	v_lshlrev_b32_e32 v228, 16, v220
	v_and_b32_e32 v229, 0xffff0000, v220
	v_lshlrev_b32_e32 v220, 16, v221
	v_and_b32_e32 v221, 0xffff0000, v221
	v_fmac_f32_e32 v3, v130, v130
	v_fmac_f32_e32 v131, v132, v132
	v_fmac_f32_e32 v133, v126, v126
	v_fmac_f32_e32 v216, v128, v128
	v_pk_fma_f32 v[124:125], v[124:125], v[222:223], v[220:221] op_sel:[0,1,0]
	global_store_dwordx2 v[212:213], v[214:215], off
	v_cvt_pk_bf16_f32 v130, v126, v127
	v_add_f32_e32 v3, v3, v131
	v_add_f32_e32 v126, v133, v216
	v_pk_fma_f32 v[122:123], v[122:123], v[222:223], v[228:229] op_sel:[0,1,0]
	v_add_f32_e32 v3, v3, v126
	v_mul_f32_e32 v126, v123, v123
	v_mul_f32_e32 v127, v125, v125
	v_fmac_f32_e32 v126, v122, v122
	v_fmac_f32_e32 v127, v124, v124
	v_add_f32_e32 v126, v126, v127
	v_add_f32_e32 v3, v3, v126
	v_lshlrev_b32_e32 v126, 16, v224
	v_and_b32_e32 v127, 0xffff0000, v224
	v_lshlrev_b32_e32 v132, 16, v225
	v_and_b32_e32 v133, 0xffff0000, v225
	v_pk_fma_f32 v[132:133], v[120:121], v[222:223], v[132:133] op_sel:[0,1,0]
	v_pk_fma_f32 v[126:127], v[118:119], v[222:223], v[126:127] op_sel:[0,1,0]
	v_mul_f32_e32 v119, v133, v133
	v_mul_f32_e32 v118, v127, v127
	v_fmac_f32_e32 v118, v126, v126
	v_fmac_f32_e32 v119, v132, v132
	v_add_f32_e32 v118, v118, v119
	v_and_b32_e32 v119, 64, v1
	v_add_f32_e32 v118, v3, v118
	v_xor_b32_e32 v3, 16, v1
	v_add_u32_e32 v120, 64, v119
	v_cmp_lt_i32_e32 vcc, v3, v120
	v_cvt_pk_bf16_f32 v131, v128, v129
	global_store_dwordx2 v[212:213], v[130:131], off offset:32
	v_cvt_pk_bf16_f32 v122, v122, v123
	v_cvt_pk_bf16_f32 v123, v124, v125
	global_store_dwordx2 v[212:213], v[122:123], off offset:256
	v_cndmask_b32_e32 v3, v1, v3, vcc
	v_lshlrev_b32_e32 v3, 2, v3
	ds_bpermute_b32 v119, v3, v118
	v_cvt_pk_bf16_f32 v122, v126, v127
	v_cvt_pk_bf16_f32 v123, v132, v133
	global_store_dwordx2 v[212:213], v[122:123], off offset:288
	s_waitcnt lgkmcnt(0)
	v_add_f32_e32 v119, v118, v119
	v_xor_b32_e32 v118, 32, v1
	v_cmp_lt_i32_e32 vcc, v118, v120
	s_nop 1
	v_cndmask_b32_e32 v118, v1, v118, vcc
	v_lshlrev_b32_e32 v118, 2, v118
	ds_bpermute_b32 v120, v118, v119
	s_and_saveexec_b64 s[8:9], s[6:7]
	s_cbranch_execz .LBB0_2494
	s_waitcnt lgkmcnt(0)
	v_add_f32_e32 v119, v119, v120
	s_lshl_b32 s42, s10, 2
	v_lshlrev_b64 v[120:121], 8, v[146:147]
	s_ashr_i32 s43, s42, 31
	v_lshl_add_u64 v[120:121], s[24:25], 0, v[120:121]
	v_lshl_add_u64 v[120:121], s[42:43], 2, v[120:121]
	s_lshl_b32 s12, s62, 2
	v_lshl_add_u64 v[120:121], v[120:121], 0, s[12:13]
	global_store_dword v[120:121], v119, off

; __device__ __forceinline__ unsigned cvt_pk_bf16(float lo, float hi) { unsigned r; asm volatile("v_cvt_pk_bf16_f32 %0, %1, %2" : "=v"(r) : "v"(lo), "v"(hi)); return r; }
;     __device__ __forceinline__ void operator()(const f32x4 (&acc)[2][2][4][2], const Unit& u, int wr, int wc, int fr, int fq) const {
;     ...
;         for (int ai = 0; ai < 2; ++ai) { u32x2 xw4[4][2][2];
; #pragma unroll
;             for (int m = 0; m < 4; ++m)
; #pragma unroll
;                 for (int bj = 0; bj < 2; ++bj)
; #pragma unroll
;                     for (int n = 0; n < 2; ++n) xw4[m][bj][n] = *(const u32x2*)(H1B + (size_t)(row0 + ai * HALF + m * 16) * 4096 + col0 + bj * HALF + n * 16);
; #pragma unroll
;             for (int m = 0; m < 4; ++m) { const int row = row0 + ai * HALF + m * 16; const float s = sc8[ai][m];
;                 float ss = 0.f;
; #pragma unroll
;                 for (int bj = 0; bj < 2; ++bj)
; #pragma unroll
;                     for (int n = 0; n < 2; ++n) { const int c = col0 + bj * HALF + n * 16; bf16_t* hp = H1B + (size_t)row * 4096 + c;
;                         const u32x2 xw = xw4[m][bj][n]; f32x4 x; x[0] = __builtin_bit_cast(float, xw.x << 16); x[1] = __builtin_bit_cast(float, xw.x & 0xffff0000u); x[2] = __builtin_bit_cast(float, xw.y << 16); x[3] = __builtin_bit_cast(float, xw.y & 0xffff0000u);
;                         const f32x4 v = x + acc[ai][bj][m][n] * s;
;                         u32x2 w; w.x = cvt_pk_bf16(v[0], v[1]); w.y = cvt_pk_bf16(v[2], v[3]); *(u32x2*)hp = w;
;                         ss += (v[0] * v[0] + v[1] * v[1]) + (v[2] * v[2] + v[3] * v[3]); }
;                 ss += __shfl_xor(ss, 16); ss += __shfl_xor(ss, 32);
;                 if (fq == 0) SSQ2[(size_t)row * 64 + u.pn * 4 + wc] = ss; } }
.LBB0_2500:
	s_or_b64 exec, exec, s[8:9]
	v_lshlrev_b64 v[100:101], 13, v[160:161]
	s_waitcnt lgkmcnt(0)
	v_lshl_add_u64 v[70:71], v[164:165], 0, v[100:101]
	global_load_dwordx2 v[102:103], v[70:71], off nt
	global_load_dwordx2 v[104:105], v[70:71], off offset:32 nt
	global_load_dwordx2 v[106:107], v[70:71], off offset:256 nt
	global_load_dwordx2 v[108:109], v[70:71], off offset:288 nt
	v_lshlrev_b64 v[96:97], 13, v[156:157]
	v_lshlrev_b64 v[86:87], 13, v[152:153]
	v_lshlrev_b64 v[76:77], 13, v[148:149]
	v_lshl_add_u64 v[70:71], v[164:165], 0, v[96:97]
	v_lshl_add_u64 v[72:73], v[164:165], 0, v[86:87]
	v_lshl_add_u64 v[110:111], v[164:165], 0, v[76:77]
	global_load_dwordx2 v[98:99], v[70:71], off nt
	global_load_dwordx2 v[94:95], v[70:71], off offset:32 nt
	global_load_dwordx2 v[92:93], v[70:71], off offset:256 nt
	global_load_dwordx2 v[90:91], v[70:71], off offset:288 nt
	global_load_dwordx2 v[88:89], v[72:73], off nt
	global_load_dwordx2 v[84:85], v[72:73], off offset:32 nt
	global_load_dwordx2 v[82:83], v[72:73], off offset:256 nt
	global_load_dwordx2 v[80:81], v[72:73], off offset:288 nt
	global_load_dwordx2 v[78:79], v[110:111], off nt
	global_load_dwordx2 v[74:75], v[110:111], off offset:32 nt
	s_nop 0
	global_load_dwordx2 v[72:73], v[110:111], off offset:256 nt
	global_load_dwordx2 v[70:71], v[110:111], off offset:288 nt
	v_lshl_add_u64 v[100:101], s[22:23], 0, v[100:101]
	v_lshl_add_u64 v[100:101], v[4:5], 1, v[100:101]
	s_waitcnt vmcnt(15)
	v_lshlrev_b32_e32 v110, 16, v102
	v_and_b32_e32 v111, 0xffff0000, v102
	v_lshlrev_b32_e32 v102, 16, v103
	v_and_b32_e32 v103, 0xffff0000, v103
	s_waitcnt vmcnt(14)
	v_lshlrev_b32_e32 v112, 16, v104
	v_and_b32_e32 v113, 0xffff0000, v104
	v_lshlrev_b32_e32 v104, 16, v105
	v_and_b32_e32 v105, 0xffff0000, v105
	s_waitcnt vmcnt(13)
	v_lshlrev_b32_e32 v114, 16, v106
	v_and_b32_e32 v115, 0xffff0000, v106
	v_lshlrev_b32_e32 v106, 16, v107
	v_and_b32_e32 v107, 0xffff0000, v107
	s_waitcnt vmcnt(12)
	v_lshlrev_b32_e32 v116, 16, v108
	v_and_b32_e32 v117, 0xffff0000, v108
	v_pk_fma_f32 v[68:69], v[68:69], v[162:163], v[102:103] op_sel:[0,1,0]
	v_pk_fma_f32 v[66:67], v[66:67], v[162:163], v[110:111] op_sel:[0,1,0]
	v_pk_fma_f32 v[64:65], v[64:65], v[162:163], v[104:105] op_sel:[0,1,0]
	v_pk_fma_f32 v[62:63], v[62:63], v[162:163], v[112:113] op_sel:[0,1,0]
	v_lshlrev_b32_e32 v108, 16, v109
	v_and_b32_e32 v109, 0xffff0000, v109
	v_pk_fma_f32 v[60:61], v[60:61], v[162:163], v[106:107] op_sel:[0,1,0]
	v_pk_fma_f32 v[58:59], v[58:59], v[162:163], v[114:115] op_sel:[0,1,0]
	v_pk_fma_f32 v[102:103], v[54:55], v[162:163], v[116:117] op_sel:[0,1,0]
	v_cvt_pk_bf16_f32 v54, v66, v67
	v_cvt_pk_bf16_f32 v55, v68, v69
	v_mul_f32_e32 v67, v67, v67
	v_mul_f32_e32 v69, v69, v69
	v_mul_f32_e32 v104, v63, v63
	v_mul_f32_e32 v105, v65, v65
	v_pk_fma_f32 v[56:57], v[56:57], v[162:163], v[108:109] op_sel:[0,1,0]
	v_mul_f32_e32 v106, v59, v59
	v_mul_f32_e32 v107, v61, v61
	v_fmac_f32_e32 v67, v66, v66
	v_fmac_f32_e32 v69, v68, v68
	v_fmac_f32_e32 v104, v62, v62
	v_fmac_f32_e32 v105, v64, v64
	v_mul_f32_e32 v108, v103, v103
	v_mul_f32_e32 v109, v57, v57
	global_store_dwordx2 v[100:101], v[54:55], off
	v_cvt_pk_bf16_f32 v54, v62, v63
	v_fmac_f32_e32 v106, v58, v58
	v_fmac_f32_e32 v107, v60, v60
	v_add_f32_e32 v55, v67, v69
	v_add_f32_e32 v62, v104, v105
	v_fmac_f32_e32 v108, v102, v102
	v_fmac_f32_e32 v109, v56, v56
	v_add_f32_e32 v63, v106, v107
	v_add_f32_e32 v55, v55, v62
	v_add_f32_e32 v55, v55, v63
	v_add_f32_e32 v62, v108, v109
	v_add_f32_e32 v62, v55, v62
	ds_bpermute_b32 v63, v3, v62
	v_cvt_pk_bf16_f32 v55, v64, v65
	global_store_dwordx2 v[100:101], v[54:55], off offset:32
	v_cvt_pk_bf16_f32 v58, v58, v59
	v_cvt_pk_bf16_f32 v59, v60, v61
	s_waitcnt lgkmcnt(0)
	v_add_f32_e32 v54, v62, v63
	ds_bpermute_b32 v55, v118, v54
	global_store_dwordx2 v[100:101], v[58:59], off offset:256
	v_cvt_pk_bf16_f32 v58, v102, v103
	v_cvt_pk_bf16_f32 v59, v56, v57
	global_store_dwordx2 v[100:101], v[58:59], off offset:288
	s_and_saveexec_b64 s[8:9], s[6:7]
	s_cbranch_execz .LBB0_2502
	s_waitcnt lgkmcnt(0)
	v_add_f32_e32 v56, v54, v55
	s_lshl_b32 s42, s10, 2
	v_lshlrev_b64 v[54:55], 8, v[160:161]
	s_ashr_i32 s43, s42, 31
	v_lshl_add_u64 v[54:55], s[24:25], 0, v[54:55]
	v_lshl_add_u64 v[54:55], s[42:43], 2, v[54:55]
	s_lshl_b32 s12, s62, 2
	v_lshl_add_u64 v[54:55], v[54:55], 0, s[12:13]
	global_store_dword v[54:55], v56, off
